# grid-barrier poll cadence: three polls of the release word in flight (a third of a round trip apart) instead of two
# speedup vs baseline: 1.0047x; 1.0047x over previous
; __device__ __forceinline__ unsigned xb_ld(unsigned* p)              { return __hip_atomic_load(p, __ATOMIC_RELAXED, __HIP_MEMORY_SCOPE_AGENT); }
; __device__ __forceinline__ unsigned xb_add(unsigned* p, unsigned v) { return __hip_atomic_fetch_add(p, v, __ATOMIC_RELAXED, __HIP_MEMORY_SCOPE_AGENT); }
; #define XB_SPIN(cond, bar) do { unsigned _sp = 0; while (cond) { __builtin_amdgcn_s_sleep(1); \
;     if ((++_sp & 255u) == 0u) { if (xb_ld(&(bar)[XB_TMO])) break; if (_sp > XB_SPIN_CAP) { atomicAdd(&(bar)[XB_TMO], 1u); break; } } } } while (0)
; __device__ __forceinline__ void xcd_barrier(const XcdBarrier& b) {
;     ...
;             else XB_SPIN(xb_ld(&bar[XB_TOPGEN]) == tg, bar);
;             __builtin_amdgcn_fence(__ATOMIC_ACQUIRE, "agent");
;             xb_add(&bar[XB_XGEN(b.x)], 1u);
;             asm volatile("s_waitcnt vmcnt(0)" ::: "memory");
;         } else {
;             XB_SPIN(xb_ld(&bar[XB_XGEN(b.x)]) == gen, bar);
.Lmy_bar_spin:
	global_load_dword v5, v99, s[2:3] sc1
	s_sleep 3
	global_load_dword v6, v99, s[2:3] sc1
	s_sleep 3
	global_load_dword v7, v99, s[2:3] sc1
.Lmy_bar_loop:
	s_waitcnt vmcnt(2)
	v_readfirstlane_b32 s11, v5
	s_cmp_ge_u32 s11, s7
	s_cbranch_scc1 .Lmy_bar_done
	global_load_dword v5, v99, s[2:3] sc1
	s_waitcnt vmcnt(2)
	v_readfirstlane_b32 s11, v6
	s_cmp_ge_u32 s11, s7
	s_cbranch_scc1 .Lmy_bar_done
	global_load_dword v6, v99, s[2:3] sc1
	s_waitcnt vmcnt(2)
	v_readfirstlane_b32 s11, v7
	s_cmp_ge_u32 s11, s7
	s_cbranch_scc1 .Lmy_bar_done
	global_load_dword v7, v99, s[2:3] sc1
	s_add_i32 s10, s10, 1
	s_cmp_lt_u32 s10, 0x10000
	s_cbranch_scc1 .Lmy_bar_loop
